# GATE: next trip's 8 y/z loads prefetched into spare registers during the current trip's compute
# speedup vs baseline: 1.0030x; 1.0006x over previous
; __device__ __forceinline__ void gate_phase(const Ctx& c) {
;     ...
;     for (int it0 = c.gw; it0 < NIT; it0 += U * c.ngw) {
;         u32x4 yv[U], zv[U];
; #pragma unroll
;         for (int u = 0; u < U; ++u) {
;             const int it = it0 + u * c.ngw;
;             if (it < NIT) { const int row = it >> 2, col = (it & 3) * 512 + c.lane * 8;
;                 yv[u] = *(const u32x4*)(XBC + (size_t)row * CONVD + col); zv[u] = *(const u32x4*)(Z + (size_t)row * DIN + col); }
;             else { yv[u] = (u32x4){0u, 0u, 0u, 0u}; zv[u] = yv[u]; }
.LBB0_111:
	s_cmp_lt_i32 s56, 7
	s_mov_b64 s[2:3], -1
	s_cbranch_scc1 .LBB0_232
	v_readlane_b32 s22, v251, 58
	v_writelane_b32 v254, s88, 16
	v_readlane_b32 s40, v253, 53
	v_readlane_b32 s23, v251, 59
	v_writelane_b32 v254, s89, 17
	s_cmp_gt_i32 s56, 7
	v_readlane_b32 s44, v253, 57
	v_readlane_b32 s45, v253, 58
	v_readlane_b32 s23, v253, 32
	v_readlane_b32 s41, v253, 54
	v_readlane_b32 s42, v253, 55
	v_readlane_b32 s43, v253, 56
	v_readlane_b32 s46, v253, 59
	v_readlane_b32 s47, v253, 60
	v_readlane_b32 s48, v253, 61
	v_readlane_b32 s49, v253, 62
	v_readlane_b32 s50, v253, 63
	v_readlane_b32 s51, v254, 0
	v_readlane_b32 s52, v254, 1
	v_readlane_b32 s53, v254, 2
	v_readlane_b32 s54, v254, 3
	v_readlane_b32 s55, v254, 4
	s_cbranch_scc0 .LBB0_135
	v_readlane_b32 s2, v254, 16
	s_cmp_gt_i32 s2, 0x20fff
	v_readlane_b32 s3, v254, 17
	s_cbranch_scc1 .LBB0_134
	v_and_b32_e32 v0, 64, v234
	v_add_u32_e32 v0, 64, v0
	v_xor_b32_e32 v1, 1, v234
	v_cmp_lt_i32_e32 vcc, v1, v0
	s_add_u32 s12, s90, 0x13488000
	s_addc_u32 s13, s91, 0
	v_cndmask_b32_e32 v1, v234, v1, vcc
	v_lshlrev_b32_e32 v3, 2, v1
	v_xor_b32_e32 v1, 2, v234
	v_cmp_lt_i32_e32 vcc, v1, v0
	s_add_u32 s14, s90, 0xb088000
	s_addc_u32 s15, s91, 0
	v_cndmask_b32_e32 v1, v234, v1, vcc
	v_lshlrev_b32_e32 v36, 2, v1
	v_xor_b32_e32 v1, 4, v234
	v_cmp_lt_i32_e32 vcc, v1, v0
	s_lshl_b32 s2, s92, 9
	v_readlane_b32 s3, v253, 31
	v_cndmask_b32_e32 v1, v234, v1, vcc
	v_lshlrev_b32_e32 v37, 2, v1
	v_xor_b32_e32 v1, 8, v234
	v_cmp_lt_i32_e32 vcc, v1, v0
	s_add_i32 s16, s3, s2
	v_readlane_b32 s2, v254, 16
	v_cndmask_b32_e32 v1, v234, v1, vcc
	v_lshlrev_b32_e32 v38, 2, v1
	v_xor_b32_e32 v1, 16, v234
	v_cmp_lt_i32_e32 vcc, v1, v0
	v_lshlrev_b32_e32 v41, 3, v162
	s_mov_b32 s10, s2
	v_cndmask_b32_e32 v1, v234, v1, vcc
	v_lshlrev_b32_e32 v39, 2, v1
	v_xor_b32_e32 v1, 32, v234
	v_cmp_lt_i32_e32 vcc, v1, v0
	v_readlane_b32 s3, v254, 17
	s_nop 0
	v_cndmask_b32_e32 v0, v234, v1, vcc
	v_lshlrev_b32_e32 v40, 2, v0
	s_and_b32 s4, s16, 0x600
	v_or_b32_e32 v1, s4, v41
	v_lshlrev_b32_e32 v52, 2, v1
	v_readlane_b32 s56, v251, 24
	v_readlane_b32 s57, v251, 25
	s_nop 4
	global_load_dwordx4 v[64:67], v52, s[56:57]
	global_load_dwordx4 v[68:71], v52, s[56:57] offset:16
	v_lshlrev_b32_e32 v0, 1, v1
	s_mov_b32 s48, s10
	s_cmp_lt_i32 s48, 0x21000
	s_cbranch_scc0 .Lgp_pre
	s_ashr_i32 s49, s48, 2
	s_mul_i32 s50, s49, 0x1800
	s_mul_hi_i32 s51, s49, 0x1800
	s_add_u32 s50, s12, s50
	s_addc_u32 s51, s13, s51
	s_ashr_i32 s53, s49, 31
	s_mov_b32 s52, s49
	s_lshl_b64 s[52:53], s[52:53], 12
	s_add_u32 s52, s14, s52
	s_addc_u32 s53, s15, s53
	global_load_dwordx4 v[72:75], v0, s[50:51]
	global_load_dwordx4 v[76:79], v0, s[52:53]
	s_add_i32 s48, s48, s22
	s_cmp_lt_i32 s48, 0x21000
	s_cbranch_scc0 .Lgp_pre
	s_ashr_i32 s49, s48, 2
	s_mul_i32 s50, s49, 0x1800
	s_mul_hi_i32 s51, s49, 0x1800
	s_add_u32 s50, s12, s50
	s_addc_u32 s51, s13, s51
	s_ashr_i32 s53, s49, 31
	s_mov_b32 s52, s49
	s_lshl_b64 s[52:53], s[52:53], 12
	s_add_u32 s52, s14, s52
	s_addc_u32 s53, s15, s53
	global_load_dwordx4 v[80:83], v0, s[50:51]
	global_load_dwordx4 v[84:87], v0, s[52:53]
	s_add_i32 s48, s48, s22
	s_cmp_lt_i32 s48, 0x21000
	s_cbranch_scc0 .Lgp_pre
	s_ashr_i32 s49, s48, 2
	s_mul_i32 s50, s49, 0x1800
	s_mul_hi_i32 s51, s49, 0x1800
	s_add_u32 s50, s12, s50
	s_addc_u32 s51, s13, s51
	s_ashr_i32 s53, s49, 31
	s_mov_b32 s52, s49
	s_lshl_b64 s[52:53], s[52:53], 12
	s_add_u32 s52, s14, s52
	s_addc_u32 s53, s15, s53
	global_load_dwordx4 v[88:91], v0, s[50:51]
	global_load_dwordx4 v[92:95], v0, s[52:53]
	s_add_i32 s48, s48, s22
	s_cmp_lt_i32 s48, 0x21000
	s_cbranch_scc0 .Lgp_pre
	s_ashr_i32 s49, s48, 2
	s_mul_i32 s50, s49, 0x1800
	s_mul_hi_i32 s51, s49, 0x1800
	s_add_u32 s50, s12, s50
	s_addc_u32 s51, s13, s51
	s_ashr_i32 s53, s49, 31
	s_mov_b32 s52, s49
	s_lshl_b64 s[52:53], s[52:53], 12
	s_add_u32 s52, s14, s52
	s_addc_u32 s53, s15, s53
	global_load_dwordx4 v[96:99], v0, s[50:51]
	global_load_dwordx4 v[100:103], v0, s[52:53]
.Lgp_pre:
	s_branch .LBB0_116
.LBB0_115:
	s_add_i32 s2, s17, s22
	s_add_i32 s2, s2, s22
	s_add_i32 s10, s2, s22
	s_add_i32 s16, s16, s23
	s_cmp_gt_i32 s10, 0x20fff
	s_cbranch_scc1 .LBB0_134
.LBB0_116:
	s_waitcnt vmcnt(0)
	s_ashr_i32 s2, s10, 2
	s_and_b32 s3, s16, 0x600
	v_or_b32_e32 v1, s3, v41
	s_ashr_i32 s3, s2, 31
	s_mul_i32 s4, s2, 0x1800
	s_mul_hi_i32 s5, s2, 0x1800
	s_add_u32 s4, s12, s4
	s_addc_u32 s5, s13, s5
	s_lshl_b64 s[2:3], s[2:3], 12
	v_lshlrev_b32_e32 v0, 1, v1
	s_add_u32 s8, s14, s2
	s_addc_u32 s9, s15, s3
	s_add_i32 s17, s10, s22
	s_cmp_lt_i32 s17, 0x21000
	s_cselect_b64 s[6:7], -1, 0
	s_mov_b64 s[2:3], -1
	s_and_b64 vcc, exec, s[6:7]
	s_cbranch_vccnz .LBB0_118
	s_mov_b64 s[2:3], 0
.LBB0_118:
	v_mov_b32_e32 v24, 0
	s_andn2_b64 vcc, exec, s[2:3]
	v_mov_b32_e32 v25, 0
	v_mov_b32_e32 v26, 0
	v_mov_b32_e32 v27, 0
	v_mov_b32_e32 v20, 0
	v_mov_b32_e32 v21, 0
	v_mov_b32_e32 v22, 0
	v_mov_b32_e32 v23, 0
	s_cbranch_vccnz .LBB0_120
	s_ashr_i32 s2, s17, 2
	s_ashr_i32 s3, s2, 31
	s_mul_i32 s4, s2, 0x1800
	s_mul_hi_i32 s5, s2, 0x1800
	s_add_u32 s4, s12, s4
	s_addc_u32 s5, s13, s5
	s_lshl_b64 s[2:3], s[2:3], 12
	s_add_u32 s2, s14, s2
	s_addc_u32 s3, s15, s3
.LBB0_120:
	v_readlane_b32 s2, v253, 22
	s_add_i32 s19, s2, s10
	s_cmp_lt_i32 s19, 0x21000
	s_cselect_b64 s[4:5], -1, 0
	s_mov_b64 s[2:3], -1
	s_and_b64 vcc, exec, s[4:5]
	s_cbranch_vccnz .LBB0_122
	s_mov_b64 s[2:3], 0
.LBB0_122:
	v_mov_b32_e32 v16, 0
	s_andn2_b64 vcc, exec, s[2:3]
	v_mov_b32_e32 v17, 0
	v_mov_b32_e32 v18, 0
	v_mov_b32_e32 v19, 0
	v_mov_b32_e32 v12, 0
	v_mov_b32_e32 v13, 0
	v_mov_b32_e32 v14, 0
	v_mov_b32_e32 v15, 0
	s_cbranch_vccnz .LBB0_124
	s_ashr_i32 s2, s19, 2
	s_ashr_i32 s3, s2, 31
	s_mul_i32 s18, s2, 0x1800
	s_mul_hi_i32 s11, s2, 0x1800
	s_add_u32 s20, s12, s18
	s_addc_u32 s21, s13, s11
	s_lshl_b64 s[2:3], s[2:3], 12
	s_add_u32 s2, s14, s2
	s_addc_u32 s3, s15, s3
.LBB0_124:
	s_mul_i32 s18, s28, 24
	s_add_i32 s18, s18, s10
	s_cmp_lt_i32 s18, 0x21000
	s_cselect_b64 s[2:3], -1, 0
	s_mov_b64 s[10:11], -1
	s_and_b64 vcc, exec, s[2:3]
	s_cbranch_vccnz .LBB0_126
	s_mov_b64 s[10:11], 0

; __device__ __forceinline__ unsigned cvt_pk_bf16(float lo, float hi) { f32x2 v = {lo, hi}; bf16x2_t b = __builtin_convertvector(v, bf16x2_t); return __builtin_bit_cast(unsigned, b); }
; __device__ __forceinline__ float bflo(unsigned w) { return __uint_as_float(w << 16); }
; __device__ __forceinline__ float bfhi(unsigned w) { return __uint_as_float(w & 0xffff0000u); }
; __device__ __forceinline__ float silu_f(float g) { return g * __builtin_amdgcn_rcpf(1.0f + __expf(-g)); }
; __device__ __forceinline__ void gate_phase(const Ctx& c) {
;     ...
;     for (int it0 = c.gw; it0 < NIT; it0 += U * c.ngw) {
;         u32x4 yv[U], zv[U];
; #pragma unroll
;         for (int u = 0; u < U; ++u) {
;             const int it = it0 + u * c.ngw;
;             if (it < NIT) { const int row = it >> 2, col = (it & 3) * 512 + c.lane * 8;
;                 yv[u] = *(const u32x4*)(XBC + (size_t)row * CONVD + col); zv[u] = *(const u32x4*)(Z + (size_t)row * DIN + col); }
;             else { yv[u] = (u32x4){0u, 0u, 0u, 0u}; zv[u] = yv[u]; }
;         }
; #pragma unroll
;         for (int u = 0; u < U; ++u) {
;             const int it = it0 + u * c.ngw;
;             if (it < NIT) {
;                 const int row = it >> 2, col = (it & 3) * 512 + c.lane * 8;
;                 float y[8] = {bflo(yv[u].x), bfhi(yv[u].x), bflo(yv[u].y), bfhi(yv[u].y), bflo(yv[u].z), bfhi(yv[u].z), bflo(yv[u].w), bfhi(yv[u].w)};
;                 const float z[8] = {bflo(zv[u].x), bfhi(zv[u].x), bflo(zv[u].y), bfhi(zv[u].y), bflo(zv[u].z), bfhi(zv[u].z), bflo(zv[u].w), bfhi(zv[u].w)};
;                 float ss = 0.f;
; #pragma unroll
;                 for (int j = 0; j < 8; ++j) { y[j] *= silu_f(z[j]); ss += y[j] * y[j]; }
;                 const float rs = rsqrtf(wave_sum(ss) * (1.0f / 512.0f) + EPS);
;                 const f32x4 n0 = *(const f32x4*)(nw + col), n1 = *(const f32x4*)(nw + col + 4);
;                 u32x4 o; o.x = cvt_pk_bf16(y[0] * rs * n0[0], y[1] * rs * n0[1]); o.y = cvt_pk_bf16(y[2] * rs * n0[2], y[3] * rs * n0[3]);
;                 o.z = cvt_pk_bf16(y[4] * rs * n1[0], y[5] * rs * n1[1]); o.w = cvt_pk_bf16(y[6] * rs * n1[2], y[7] * rs * n1[3]);
;                 *(u32x4*)(Z + (size_t)row * DIN + col) = o;
.LBB0_128:
	v_mov_b64_e32 v[28:29], v[72:73]
	v_mov_b64_e32 v[30:31], v[74:75]
	v_mov_b64_e32 v[32:33], v[76:77]
	v_mov_b64_e32 v[34:35], v[78:79]
	v_mov_b64_e32 v[20:21], v[80:81]
	v_mov_b64_e32 v[22:23], v[82:83]
	v_mov_b64_e32 v[24:25], v[84:85]
	v_mov_b64_e32 v[26:27], v[86:87]
	v_mov_b64_e32 v[12:13], v[88:89]
	v_mov_b64_e32 v[14:15], v[90:91]
	v_mov_b64_e32 v[16:17], v[92:93]
	v_mov_b64_e32 v[18:19], v[94:95]
	v_mov_b64_e32 v[4:5], v[96:97]
	v_mov_b64_e32 v[6:7], v[98:99]
	v_mov_b64_e32 v[8:9], v[100:101]
	v_mov_b64_e32 v[10:11], v[102:103]
	s_add_i32 s48, s17, s22
	s_add_i32 s48, s48, s22
	s_add_i32 s48, s48, s22
	s_cmp_lt_i32 s48, 0x21000
	s_cbranch_scc0 .Lgp_nxt
	s_ashr_i32 s49, s48, 2
	s_mul_i32 s50, s49, 0x1800
	s_mul_hi_i32 s51, s49, 0x1800
	s_add_u32 s50, s12, s50
	s_addc_u32 s51, s13, s51
	s_ashr_i32 s53, s49, 31
	s_mov_b32 s52, s49
	s_lshl_b64 s[52:53], s[52:53], 12
	s_add_u32 s52, s14, s52
	s_addc_u32 s53, s15, s53
	global_load_dwordx4 v[72:75], v0, s[50:51]
	global_load_dwordx4 v[76:79], v0, s[52:53]
	s_add_i32 s48, s48, s22
	s_cmp_lt_i32 s48, 0x21000
	s_cbranch_scc0 .Lgp_nxt
	s_ashr_i32 s49, s48, 2
	s_mul_i32 s50, s49, 0x1800
	s_mul_hi_i32 s51, s49, 0x1800
	s_add_u32 s50, s12, s50
	s_addc_u32 s51, s13, s51
	s_ashr_i32 s53, s49, 31
	s_mov_b32 s52, s49
	s_lshl_b64 s[52:53], s[52:53], 12
	s_add_u32 s52, s14, s52
	s_addc_u32 s53, s15, s53
	global_load_dwordx4 v[80:83], v0, s[50:51]
	global_load_dwordx4 v[84:87], v0, s[52:53]
	s_add_i32 s48, s48, s22
	s_cmp_lt_i32 s48, 0x21000
	s_cbranch_scc0 .Lgp_nxt
	s_ashr_i32 s49, s48, 2
	s_mul_i32 s50, s49, 0x1800
	s_mul_hi_i32 s51, s49, 0x1800
	s_add_u32 s50, s12, s50
	s_addc_u32 s51, s13, s51
	s_ashr_i32 s53, s49, 31
	s_mov_b32 s52, s49
	s_lshl_b64 s[52:53], s[52:53], 12
	s_add_u32 s52, s14, s52
	s_addc_u32 s53, s15, s53
	global_load_dwordx4 v[88:91], v0, s[50:51]
	global_load_dwordx4 v[92:95], v0, s[52:53]
	s_add_i32 s48, s48, s22
	s_cmp_lt_i32 s48, 0x21000
	s_cbranch_scc0 .Lgp_nxt
	s_ashr_i32 s49, s48, 2
	s_mul_i32 s50, s49, 0x1800
	s_mul_hi_i32 s51, s49, 0x1800
	s_add_u32 s50, s12, s50
	s_addc_u32 s51, s13, s51
	s_ashr_i32 s53, s49, 31
	s_mov_b32 s52, s49
	s_lshl_b64 s[52:53], s[52:53], 12
	s_add_u32 s52, s14, s52
	s_addc_u32 s53, s15, s53
	global_load_dwordx4 v[96:99], v0, s[50:51]
	global_load_dwordx4 v[100:103], v0, s[52:53]
.Lgp_nxt:
	v_lshlrev_b32_e32 v50, 16, v35
	v_and_b32_e32 v51, 0xffff0000, v35
	v_mul_f32_e32 v35, 0xbfb8aa3b, v50
	v_exp_f32_e32 v35, v35
	v_mul_f32_e32 v42, 0xbfb8aa3b, v51
	v_exp_f32_e32 v42, v42
	v_lshlrev_b32_e32 v52, 2, v1
	v_add_f32_e32 v1, 1.0, v35
	v_rcp_f32_e32 v54, v1
	v_add_f32_e32 v1, 1.0, v42
	v_rcp_f32_e32 v55, v1
	v_lshlrev_b32_e32 v56, 16, v31
	v_and_b32_e32 v57, 0xffff0000, v31
	v_readlane_b32 s48, v251, 16
	v_pk_mul_f32 v[50:51], v[54:55], v[50:51]
	v_lshlrev_b32_e32 v54, 16, v34
	v_and_b32_e32 v55, 0xffff0000, v34
	v_mul_f32_e32 v1, 0xbfb8aa3b, v54
	v_exp_f32_e32 v1, v1
	v_mul_f32_e32 v31, 0xbfb8aa3b, v55
	v_exp_f32_e32 v31, v31
	v_pk_mul_f32 v[34:35], v[50:51], v[56:57]
	v_add_f32_e32 v1, 1.0, v1
	v_rcp_f32_e32 v50, v1
	v_add_f32_e32 v1, 1.0, v31
	v_rcp_f32_e32 v51, v1
	v_readlane_b32 s56, v251, 24
	v_readlane_b32 s57, v251, 25
	s_nop 4
	v_lshlrev_b32_e32 v58, 16, v30
	v_and_b32_e32 v59, 0xffff0000, v30
	v_pk_mul_f32 v[30:31], v[50:51], v[54:55]
	v_lshlrev_b32_e32 v50, 16, v33
	v_and_b32_e32 v51, 0xffff0000, v33
	v_mul_f32_e32 v1, 0xbfb8aa3b, v50
	v_exp_f32_e32 v1, v1
	v_mul_f32_e32 v33, 0xbfb8aa3b, v51
	v_exp_f32_e32 v33, v33
	v_pk_mul_f32 v[54:55], v[30:31], v[58:59]
	v_add_f32_e32 v1, 1.0, v1
	v_rcp_f32_e32 v30, v1
	v_add_f32_e32 v1, 1.0, v33
	v_rcp_f32_e32 v31, v1
	v_lshlrev_b32_e32 v60, 16, v29
	v_and_b32_e32 v61, 0xffff0000, v29
	v_lshlrev_b32_e32 v62, 16, v28
	v_pk_mul_f32 v[30:31], v[30:31], v[50:51]
	v_lshlrev_b32_e32 v50, 16, v32
	v_and_b32_e32 v51, 0xffff0000, v32
	v_mul_f32_e32 v1, 0xbfb8aa3b, v50
	v_exp_f32_e32 v1, v1
	v_mul_f32_e32 v29, 0xbfb8aa3b, v51
	v_exp_f32_e32 v29, v29
	v_pk_mul_f32 v[32:33], v[30:31], v[60:61]
	v_add_f32_e32 v1, 1.0, v1
	v_rcp_f32_e32 v30, v1
	v_add_f32_e32 v1, 1.0, v29
	v_rcp_f32_e32 v31, v1
	v_and_b32_e32 v63, 0xffff0000, v28
	v_pk_mul_f32 v[60:61], v[32:33], v[32:33]
	v_pk_mul_f32 v[58:59], v[54:55], v[54:55]
	v_pk_mul_f32 v[28:29], v[30:31], v[50:51]
	v_pk_mul_f32 v[56:57], v[34:35], v[34:35]
	v_pk_mul_f32 v[30:31], v[28:29], v[62:63]
	v_mov_b32_e32 v53, v2
	v_pk_mul_f32 v[28:29], v[30:31], v[30:31]
	v_readlane_b32 s49, v251, 17
	v_add_f32_e32 v1, v28, v29
	v_add_f32_e32 v1, v60, v1
	v_add_f32_e32 v1, v61, v1
	v_add_f32_e32 v1, v58, v1
	v_add_f32_e32 v1, v59, v1
	v_add_f32_e32 v1, v56, v1
	v_add_f32_e32 v1, v57, v1
	s_nop 1
	v_add_f32_dpp v28, v1, v1 quad_perm:[1,0,3,2] row_mask:0xf bank_mask:0xf
	s_nop 1
	v_add_f32_dpp v28, v28, v28 quad_perm:[2,3,0,1] row_mask:0xf bank_mask:0xf
	s_nop 1
	v_add_f32_dpp v28, v28, v28 row_half_mirror row_mask:0xf bank_mask:0xf
	s_nop 1
	v_add_f32_dpp v28, v28, v28 row_mirror row_mask:0xf bank_mask:0xf
	s_nop 1
	v_add_f32_dpp v28, v28, v28 row_bcast:15 row_mask:0xa bank_mask:0xf
	s_nop 1
	v_add_f32_dpp v28, v28, v28 row_bcast:31 row_mask:0xc bank_mask:0xf
	s_nop 0
	v_readlane_b32 s32, v28, 63
	s_nop 1
	v_mov_b32_e32 v28, s32
	v_readlane_b32 s50, v251, 18
	v_readlane_b32 s51, v251, 19
	v_readlane_b32 s52, v251, 20
	v_readlane_b32 s53, v251, 21
	v_readlane_b32 s54, v251, 22
	v_readlane_b32 s55, v251, 23
	v_readlane_b32 s58, v251, 26
	v_readlane_b32 s59, v251, 27
	v_readlane_b32 s60, v251, 28
	v_readlane_b32 s61, v251, 29
	v_readlane_b32 s62, v251, 30
	v_readlane_b32 s63, v251, 31
	v_mov_b32_e32 v1, v2
	v_lshl_add_u64 v[50:51], s[8:9], 0, v[0:1]
	v_fmamk_f32 v28, v28, 0x3b000000, v228
	v_mul_f32_e32 v29, 0x4b800000, v28
	v_cmp_gt_f32_e32 vcc, s37, v28
	s_nop 1
	v_cndmask_b32_e32 v28, v28, v29, vcc
	v_rsq_f32_e32 v56, v28
	v_lshl_add_u64 v[28:29], s[56:57], 0, v[52:53]
	v_mul_f32_e32 v1, 0x45800000, v56
	v_cndmask_b32_e32 v52, v56, v1, vcc
	v_pk_mul_f32 v[30:31], v[30:31], v[52:53] op_sel_hi:[1,0]
	v_pk_mul_f32 v[32:33], v[32:33], v[52:53] op_sel_hi:[1,0]
	v_pk_mul_f32 v[30:31], v[64:65], v[30:31]
	v_pk_mul_f32 v[32:33], v[66:67], v[32:33]
	v_cvt_pk_bf16_f32 v30, v30, v31
	v_cvt_pk_bf16_f32 v31, v32, v33
	v_pk_mul_f32 v[32:33], v[54:55], v[52:53] op_sel_hi:[1,0]
	v_pk_mul_f32 v[34:35], v[34:35], v[52:53] op_sel_hi:[1,0]
	v_pk_mul_f32 v[32:33], v[68:69], v[32:33]
	v_pk_mul_f32 v[34:35], v[70:71], v[34:35]
	v_cvt_pk_bf16_f32 v32, v32, v33
	v_cvt_pk_bf16_f32 v33, v34, v35
	s_andn2_b64 vcc, exec, s[6:7]
	global_store_dwordx4 v[50:51], v[30:33], off
	s_cbranch_vccnz .LBB0_131
; __device__ __forceinline__ unsigned cvt_pk_bf16(float lo, float hi) { f32x2 v = {lo, hi}; bf16x2_t b = __builtin_convertvector(v, bf16x2_t); return __builtin_bit_cast(unsigned, b); }
; __device__ __forceinline__ float bflo(unsigned w) { return __uint_as_float(w << 16); }
; __device__ __forceinline__ float bfhi(unsigned w) { return __uint_as_float(w & 0xffff0000u); }
; __device__ __forceinline__ float silu_f(float g) { return g * __builtin_amdgcn_rcpf(1.0f + __expf(-g)); }
; __device__ __forceinline__ void gate_phase(const Ctx& c) {
;     ...
;         for (int u = 0; u < U; ++u) {
;             const int it = it0 + u * c.ngw;
;             if (it < NIT) {
;                 const int row = it >> 2, col = (it & 3) * 512 + c.lane * 8;
;                 float y[8] = {bflo(yv[u].x), bfhi(yv[u].x), bflo(yv[u].y), bfhi(yv[u].y), bflo(yv[u].z), bfhi(yv[u].z), bflo(yv[u].w), bfhi(yv[u].w)};
;                 const float z[8] = {bflo(zv[u].x), bfhi(zv[u].x), bflo(zv[u].y), bfhi(zv[u].y), bflo(zv[u].z), bfhi(zv[u].z), bflo(zv[u].w), bfhi(zv[u].w)};
;                 float ss = 0.f;
; #pragma unroll
;                 for (int j = 0; j < 8; ++j) { y[j] *= silu_f(z[j]); ss += y[j] * y[j]; }
;                 const float rs = rsqrtf(wave_sum(ss) * (1.0f / 512.0f) + EPS);
;                 const f32x4 n0 = *(const f32x4*)(nw + col), n1 = *(const f32x4*)(nw + col + 4);
;                 u32x4 o; o.x = cvt_pk_bf16(y[0] * rs * n0[0], y[1] * rs * n0[1]); o.y = cvt_pk_bf16(y[2] * rs * n0[2], y[3] * rs * n0[3]);
;                 o.z = cvt_pk_bf16(y[4] * rs * n1[0], y[5] * rs * n1[1]); o.w = cvt_pk_bf16(y[6] * rs * n1[2], y[7] * rs * n1[3]);
;                 *(u32x4*)(Z + (size_t)row * DIN + col) = o;
	v_lshlrev_b32_e32 v34, 16, v27
	v_and_b32_e32 v35, 0xffff0000, v27
	v_mul_f32_e32 v1, 0xbfb8aa3b, v34
	v_exp_f32_e32 v1, v1
	v_mul_f32_e32 v27, 0xbfb8aa3b, v35
	v_exp_f32_e32 v27, v27
	v_lshlrev_b32_e32 v48, 16, v23
	v_add_f32_e32 v1, 1.0, v1
	v_rcp_f32_e32 v46, v1
	v_add_f32_e32 v1, 1.0, v27
	v_rcp_f32_e32 v47, v1
	v_and_b32_e32 v49, 0xffff0000, v23
	v_lshlrev_b32_e32 v50, 16, v22
	v_pk_mul_f32 v[34:35], v[46:47], v[34:35]
	v_lshlrev_b32_e32 v46, 16, v26
	v_and_b32_e32 v47, 0xffff0000, v26
	v_mul_f32_e32 v1, 0xbfb8aa3b, v46
	v_exp_f32_e32 v1, v1
	v_mul_f32_e32 v23, 0xbfb8aa3b, v47
	v_exp_f32_e32 v23, v23
	v_pk_mul_f32 v[26:27], v[34:35], v[48:49]
	v_add_f32_e32 v1, 1.0, v1
	v_rcp_f32_e32 v34, v1
	v_add_f32_e32 v1, 1.0, v23
	v_rcp_f32_e32 v35, v1
	v_and_b32_e32 v51, 0xffff0000, v22
	v_lshlrev_b32_e32 v52, 16, v21
	v_and_b32_e32 v53, 0xffff0000, v21
	v_pk_mul_f32 v[22:23], v[34:35], v[46:47]
	v_lshlrev_b32_e32 v34, 16, v25
	v_and_b32_e32 v35, 0xffff0000, v25
	v_mul_f32_e32 v1, 0xbfb8aa3b, v34
	v_exp_f32_e32 v1, v1
	v_mul_f32_e32 v25, 0xbfb8aa3b, v35
	v_exp_f32_e32 v25, v25
	v_lshlrev_b32_e32 v54, 16, v20
	v_add_f32_e32 v1, 1.0, v1
	v_rcp_f32_e32 v46, v1
	v_add_f32_e32 v1, 1.0, v25
	v_rcp_f32_e32 v47, v1
	v_and_b32_e32 v55, 0xffff0000, v20
	v_pk_mul_f32 v[22:23], v[22:23], v[50:51]
	v_pk_mul_f32 v[48:49], v[26:27], v[26:27]
	v_pk_mul_f32 v[34:35], v[46:47], v[34:35]
	v_lshlrev_b32_e32 v46, 16, v24
	v_and_b32_e32 v47, 0xffff0000, v24
	v_mul_f32_e32 v1, 0xbfb8aa3b, v46
	v_exp_f32_e32 v1, v1
	v_mul_f32_e32 v21, 0xbfb8aa3b, v47
	v_exp_f32_e32 v21, v21
	v_pk_mul_f32 v[24:25], v[34:35], v[52:53]
	v_add_f32_e32 v1, 1.0, v1
	v_rcp_f32_e32 v34, v1
	v_add_f32_e32 v1, 1.0, v21
	v_rcp_f32_e32 v35, v1
	v_pk_mul_f32 v[52:53], v[24:25], v[24:25]
	v_pk_mul_f32 v[50:51], v[22:23], v[22:23]
	s_ashr_i32 s6, s17, 2
	v_pk_mul_f32 v[20:21], v[34:35], v[46:47]
	s_ashr_i32 s7, s6, 31
	v_pk_mul_f32 v[20:21], v[20:21], v[54:55]
	s_lshl_b64 s[6:7], s[6:7], 12
	v_pk_mul_f32 v[34:35], v[20:21], v[20:21]
	s_add_u32 s6, s14, s6
	v_add_f32_e32 v1, v34, v35
	v_add_f32_e32 v1, v52, v1
	v_add_f32_e32 v1, v53, v1
	v_add_f32_e32 v1, v50, v1
	v_add_f32_e32 v1, v51, v1
	v_add_f32_e32 v1, v48, v1
	v_add_f32_e32 v1, v49, v1
	s_nop 1
	v_add_f32_dpp v1, v1, v1 quad_perm:[1,0,3,2] row_mask:0xf bank_mask:0xf
	s_nop 1
	v_add_f32_dpp v1, v1, v1 quad_perm:[2,3,0,1] row_mask:0xf bank_mask:0xf
	s_nop 1
	v_add_f32_dpp v1, v1, v1 row_half_mirror row_mask:0xf bank_mask:0xf
	s_nop 1
	v_add_f32_dpp v1, v1, v1 row_mirror row_mask:0xf bank_mask:0xf
	s_nop 1
	v_add_f32_dpp v1, v1, v1 row_bcast:15 row_mask:0xa bank_mask:0xf
	s_nop 1
	v_add_f32_dpp v1, v1, v1 row_bcast:31 row_mask:0xc bank_mask:0xf
	s_nop 0
	v_readlane_b32 s32, v1, 63
	s_nop 1
	v_mov_b32_e32 v1, s32
	s_addc_u32 s7, s15, s7
	v_fmamk_f32 v1, v1, 0x3b000000, v228
	v_mul_f32_e32 v34, 0x4b800000, v1
	v_cmp_gt_f32_e32 vcc, s37, v1
	s_nop 1
	v_cndmask_b32_e32 v1, v1, v34, vcc
	v_rsq_f32_e32 v1, v1
	s_nop 0
	v_mul_f32_e32 v34, 0x45800000, v1
	v_cndmask_b32_e32 v34, v1, v34, vcc
	v_pk_mul_f32 v[20:21], v[20:21], v[34:35] op_sel_hi:[1,0]
	v_pk_mul_f32 v[24:25], v[24:25], v[34:35] op_sel_hi:[1,0]
	v_pk_mul_f32 v[20:21], v[64:65], v[20:21]
	v_pk_mul_f32 v[24:25], v[66:67], v[24:25]
	v_cvt_pk_bf16_f32 v20, v20, v21
	v_cvt_pk_bf16_f32 v21, v24, v25
	v_pk_mul_f32 v[22:23], v[22:23], v[34:35] op_sel_hi:[1,0]
	v_pk_mul_f32 v[24:25], v[26:27], v[34:35] op_sel_hi:[1,0]
	v_pk_mul_f32 v[22:23], v[68:69], v[22:23]
	v_pk_mul_f32 v[24:25], v[70:71], v[24:25]
	v_cvt_pk_bf16_f32 v22, v22, v23
	v_cvt_pk_bf16_f32 v23, v24, v25
	global_store_dwordx4 v0, v[20:23], s[6:7]
	s_andn2_b64 vcc, exec, s[4:5]
	s_cbranch_vccz .LBB0_132
